# gla_scan: batch-prefetch all decay LDS reads of a half into v98-161 (removes per-step LDS latency from the serial recurrence)
# baseline (speedup 1.0000x reference)
; #define LAS __attribute__((address_space(3)))
; DI void gla_scan(const Params& p, int G, LAS unsigned char* lds) {
;     ...
;     for (int e0 = blockIdx.x * 512; e0 < 16 * 8192; e0 += G * 512) {
;         const int e = e0 + tid, bh = e0 >> 13, vk = e & 8191, k = e & 63, b = bh >> 2, h = bh & 3;
;         __syncthreads();
; #pragma unroll
;         for (int i4 = 0; i4 < 4; ++i4) { const int idx = tid * 4 + 2048 * i4, n = idx >> 6, kk = idx & 63;
;             *(LAS f32x4*)(dl + idx) = *(const f32x4*)(decay + (size_t)(b * 128 + n) * 256 + h * 64 + kk); }
;         __syncthreads();
;         const float* dp = dST + (size_t)bh * 128 * 8192 + vk; bf16_t* sp = SpT + (size_t)bh * 128 * 8192 + vk;
;         float st = 0.f;
;         for (int n0 = 0; n0 < 128; n0 += 64) { float dv[64];
; #pragma unroll
;             for (int j2 = 0; j2 < 64; ++j2) dv[j2] = __builtin_nontemporal_load(dp + (size_t)(n0 + j2) * 8192);
.LBB0_434:
	s_ashr_i32 s9, s80, 8
	s_ashr_i32 s8, s80, 13
	s_and_b32 s9, s9, 0xffffff80
	s_lshl_b32 s20, s8, 8
	v_add_u32_e32 v4, s9, v12
	s_and_b32 s30, s20, 0x300
	v_ashrrev_i32_e32 v5, 31, v4
	v_lshl_add_u64 v[8:9], v[2:3], 0, s[30:31]
	v_lshlrev_b64 v[4:5], 10, v[4:5]
	v_lshl_add_u64 v[4:5], v[8:9], 0, v[4:5]
	s_waitcnt vmcnt(0)
	s_barrier
	global_load_dwordx4 v[100:103], v[4:5], off
	v_add_u32_e32 v0, s80, v10
	v_add_u32_e32 v4, s9, v14
	v_ashrrev_i32_e32 v5, 31, v4
	v_lshlrev_b64 v[4:5], 10, v[4:5]
	v_lshl_add_u64 v[4:5], v[8:9], 0, v[4:5]
	global_load_dwordx4 v[104:107], v[4:5], off
	v_add_u32_e32 v4, s9, v15
	v_ashrrev_i32_e32 v5, 31, v4
	v_lshlrev_b64 v[4:5], 10, v[4:5]
	v_lshl_add_u64 v[4:5], v[8:9], 0, v[4:5]
	global_load_dwordx4 v[108:111], v[4:5], off
	v_add_u32_e32 v4, s9, v16
	v_ashrrev_i32_e32 v5, 31, v4
	v_lshlrev_b64 v[4:5], 10, v[4:5]
	v_lshl_add_u64 v[4:5], v[8:9], 0, v[4:5]
	global_load_dwordx4 v[112:115], v[4:5], off
	s_ashr_i32 s9, s8, 31
	s_lshl_b64 s[20:21], s[8:9], 22
	s_add_u32 s22, s96, s20
	s_addc_u32 s23, s97, s21
	s_lshl_b64 s[8:9], s[8:9], 21
	s_add_u32 s20, s94, s8
	s_addc_u32 s21, s95, s9
	v_mov_b32_e32 v9, v1
	s_mov_b32 s8, 0x1f8000
	s_add_i32 s80, s80, s34
	s_cmp_lt_i32 s80, 0x20000
	v_and_b32_e32 v4, 0x1fff, v0
	v_lshlrev_b32_e32 v0, 2, v4
	v_lshl_add_u64 v[6:7], s[22:23], 0, v[0:1]
	v_add_co_u32_e32 v18, vcc, s38, v6
	s_nop 1
	v_addc_co_u32_e32 v19, vcc, 0, v7, vcc
	global_load_dword v78, v0, s[22:23] nt
	global_load_dword v77, v[18:19], off nt
	v_add_co_u32_e32 v18, vcc, s39, v6
	v_lshlrev_b32_e32 v8, 1, v4
	s_nop 0
	v_addc_co_u32_e32 v19, vcc, 0, v7, vcc
	global_load_dword v76, v[18:19], off nt
	v_add_co_u32_e32 v18, vcc, s40, v6
	v_lshl_add_u64 v[4:5], s[20:21], 0, v[8:9]
	s_nop 0
	v_addc_co_u32_e32 v19, vcc, 0, v7, vcc
	global_load_dword v75, v[18:19], off nt
	v_add_co_u32_e32 v18, vcc, s41, v6
	global_store_short v8, v1, s[20:21]
	s_nop 0
	v_addc_co_u32_e32 v19, vcc, 0, v7, vcc
	global_load_dword v74, v[18:19], off nt
	v_add_co_u32_e32 v18, vcc, s42, v6
	s_nop 1
	v_addc_co_u32_e32 v19, vcc, 0, v7, vcc
	global_load_dword v73, v[18:19], off nt
	v_add_co_u32_e32 v18, vcc, s43, v6
	s_nop 1
	v_addc_co_u32_e32 v19, vcc, 0, v7, vcc
	global_load_dword v72, v[18:19], off nt
	v_add_co_u32_e32 v18, vcc, s44, v6
	s_nop 1
	v_addc_co_u32_e32 v19, vcc, 0, v7, vcc
	global_load_dword v71, v[18:19], off nt
	v_add_co_u32_e32 v18, vcc, s45, v6
	s_nop 1
	v_addc_co_u32_e32 v19, vcc, 0, v7, vcc
	global_load_dword v70, v[18:19], off nt
	v_add_co_u32_e32 v18, vcc, s46, v6
	s_nop 1
	v_addc_co_u32_e32 v19, vcc, 0, v7, vcc
	global_load_dword v69, v[18:19], off nt
	v_add_co_u32_e32 v18, vcc, s47, v6
	s_nop 1
	v_addc_co_u32_e32 v19, vcc, 0, v7, vcc
	global_load_dword v68, v[18:19], off nt
	v_add_co_u32_e32 v18, vcc, s48, v6
	s_nop 1
	v_addc_co_u32_e32 v19, vcc, 0, v7, vcc
	global_load_dword v67, v[18:19], off nt
	v_add_co_u32_e32 v18, vcc, s49, v6
	s_nop 1
	v_addc_co_u32_e32 v19, vcc, 0, v7, vcc
	global_load_dword v66, v[18:19], off nt
	v_add_co_u32_e32 v18, vcc, s50, v6
	s_nop 1
	v_addc_co_u32_e32 v19, vcc, 0, v7, vcc
	global_load_dword v65, v[18:19], off nt
	v_add_co_u32_e32 v18, vcc, s51, v6
	s_nop 1
	v_addc_co_u32_e32 v19, vcc, 0, v7, vcc
	global_load_dword v64, v[18:19], off nt
	v_add_co_u32_e32 v18, vcc, s52, v6
	s_nop 1
	v_addc_co_u32_e32 v19, vcc, 0, v7, vcc
	global_load_dword v63, v[18:19], off nt
	v_add_co_u32_e32 v18, vcc, s53, v6
	s_nop 1
	v_addc_co_u32_e32 v19, vcc, 0, v7, vcc
	global_load_dword v62, v[18:19], off nt
	v_add_co_u32_e32 v18, vcc, s55, v6
	s_nop 1
	v_addc_co_u32_e32 v19, vcc, 0, v7, vcc
	global_load_dword v61, v[18:19], off nt
	v_add_co_u32_e32 v18, vcc, s56, v6
	s_nop 1
	v_addc_co_u32_e32 v19, vcc, 0, v7, vcc
	global_load_dword v60, v[18:19], off nt
	v_add_co_u32_e32 v18, vcc, s57, v6
	s_nop 1
	v_addc_co_u32_e32 v19, vcc, 0, v7, vcc
	global_load_dword v59, v[18:19], off nt
	v_add_co_u32_e32 v18, vcc, s58, v6
	s_nop 1
	v_addc_co_u32_e32 v19, vcc, 0, v7, vcc
	global_load_dword v58, v[18:19], off nt
	v_add_co_u32_e32 v18, vcc, s59, v6
	s_nop 1
	v_addc_co_u32_e32 v19, vcc, 0, v7, vcc
	global_load_dword v57, v[18:19], off nt
	v_add_co_u32_e32 v18, vcc, s60, v6
	s_nop 1
	v_addc_co_u32_e32 v19, vcc, 0, v7, vcc
	global_load_dword v56, v[18:19], off nt
	v_add_co_u32_e32 v18, vcc, s61, v6
	s_nop 1
	v_addc_co_u32_e32 v19, vcc, 0, v7, vcc
	global_load_dword v55, v[18:19], off nt
	v_add_co_u32_e32 v18, vcc, s62, v6
	s_nop 1
	v_addc_co_u32_e32 v19, vcc, 0, v7, vcc
	global_load_dword v54, v[18:19], off nt
	v_add_co_u32_e32 v18, vcc, s63, v6
	s_nop 1
	v_addc_co_u32_e32 v19, vcc, 0, v7, vcc
	global_load_dword v53, v[18:19], off nt
	v_add_co_u32_e32 v18, vcc, s64, v6
	s_nop 1
	v_addc_co_u32_e32 v19, vcc, 0, v7, vcc
	global_load_dword v52, v[18:19], off nt
	v_add_co_u32_e32 v18, vcc, s65, v6
	s_nop 1
	v_addc_co_u32_e32 v19, vcc, 0, v7, vcc
	global_load_dword v51, v[18:19], off nt
	v_add_co_u32_e32 v18, vcc, s66, v6
	s_nop 1
	v_addc_co_u32_e32 v19, vcc, 0, v7, vcc
	global_load_dword v50, v[18:19], off nt
	v_add_co_u32_e32 v18, vcc, s67, v6
	s_nop 1
	v_addc_co_u32_e32 v19, vcc, 0, v7, vcc
	global_load_dword v49, v[18:19], off nt
	v_add_co_u32_e32 v18, vcc, s68, v6
	s_nop 1
	v_addc_co_u32_e32 v19, vcc, 0, v7, vcc
	global_load_dword v48, v[18:19], off nt
	v_add_co_u32_e32 v18, vcc, s69, v6
	s_nop 1
	v_addc_co_u32_e32 v19, vcc, 0, v7, vcc
	global_load_dword v47, v[18:19], off nt
	v_add_co_u32_e32 v18, vcc, s70, v6
	s_nop 1
	v_addc_co_u32_e32 v19, vcc, 0, v7, vcc
	global_load_dword v46, v[18:19], off nt
	v_add_co_u32_e32 v18, vcc, s71, v6
	s_nop 1
	v_addc_co_u32_e32 v19, vcc, 0, v7, vcc
	global_load_dword v45, v[18:19], off nt
; #define LAS __attribute__((address_space(3)))
; DI bf16_t f2bf(float f) { return (bf16_t)(pk2(f, 0.f) & 0xffffu); }
; DI void gla_scan(const Params& p, int G, LAS unsigned char* lds) {
;     ...
;         for (int i4 = 0; i4 < 4; ++i4) { const int idx = tid * 4 + 2048 * i4, n = idx >> 6, kk = idx & 63;
;             *(LAS f32x4*)(dl + idx) = *(const f32x4*)(decay + (size_t)(b * 128 + n) * 256 + h * 64 + kk); }
;         __syncthreads();
;         const float* dp = dST + (size_t)bh * 128 * 8192 + vk; bf16_t* sp = SpT + (size_t)bh * 128 * 8192 + vk;
;         float st = 0.f;
;         for (int n0 = 0; n0 < 128; n0 += 64) { float dv[64];
; #pragma unroll
;             for (int j2 = 0; j2 < 64; ++j2) dv[j2] = __builtin_nontemporal_load(dp + (size_t)(n0 + j2) * 8192);
; #pragma unroll
;             for (int j2 = 0; j2 < 64; ++j2) { sp[(size_t)(n0 + j2) * 8192] = f2bf(st); st = dl[(n0 + j2) * 64 + k] * st + dv[j2]; } }
	v_add_co_u32_e32 v18, vcc, s72, v6
	s_nop 1
	v_addc_co_u32_e32 v19, vcc, 0, v7, vcc
	global_load_dword v44, v[18:19], off nt
	v_add_co_u32_e32 v18, vcc, s73, v6
	s_nop 1
	v_addc_co_u32_e32 v19, vcc, 0, v7, vcc
	global_load_dword v43, v[18:19], off nt
	v_add_co_u32_e32 v18, vcc, s78, v6
	s_nop 1
	v_addc_co_u32_e32 v19, vcc, 0, v7, vcc
	global_load_dword v42, v[18:19], off nt
	v_add_co_u32_e32 v18, vcc, s79, v6
	s_nop 1
	v_addc_co_u32_e32 v19, vcc, 0, v7, vcc
	global_load_dword v41, v[18:19], off nt
	v_add_co_u32_e32 v18, vcc, s81, v6
	s_nop 1
	v_addc_co_u32_e32 v19, vcc, 0, v7, vcc
	global_load_dword v40, v[18:19], off nt
	v_add_co_u32_e32 v18, vcc, s83, v6
	s_nop 1
	v_addc_co_u32_e32 v19, vcc, 0, v7, vcc
	global_load_dword v39, v[18:19], off nt
	v_add_co_u32_e32 v18, vcc, s84, v6
	s_nop 1
	v_addc_co_u32_e32 v19, vcc, 0, v7, vcc
	global_load_dword v38, v[18:19], off nt
	v_add_co_u32_e32 v18, vcc, s85, v6
	s_nop 1
	v_addc_co_u32_e32 v19, vcc, 0, v7, vcc
	global_load_dword v37, v[18:19], off nt
	v_add_co_u32_e32 v18, vcc, s87, v6
	s_nop 1
	v_addc_co_u32_e32 v19, vcc, 0, v7, vcc
	global_load_dword v36, v[18:19], off nt
	v_add_co_u32_e32 v18, vcc, s88, v6
	s_nop 1
	v_addc_co_u32_e32 v19, vcc, 0, v7, vcc
	global_load_dword v35, v[18:19], off nt
	v_add_co_u32_e32 v18, vcc, s89, v6
	s_nop 1
	v_addc_co_u32_e32 v19, vcc, 0, v7, vcc
	global_load_dword v34, v[18:19], off nt
	v_add_co_u32_e32 v18, vcc, s35, v6
	s_nop 1
	v_addc_co_u32_e32 v19, vcc, 0, v7, vcc
	global_load_dword v33, v[18:19], off nt
	v_add_co_u32_e32 v18, vcc, s86, v6
	s_nop 1
	v_addc_co_u32_e32 v19, vcc, 0, v7, vcc
	global_load_dword v32, v[18:19], off nt
	v_add_co_u32_e32 v18, vcc, s90, v6
	s_nop 1
	v_addc_co_u32_e32 v19, vcc, 0, v7, vcc
	global_load_dword v31, v[18:19], off nt
	v_add_co_u32_e32 v18, vcc, s91, v6
	s_nop 1
	v_addc_co_u32_e32 v19, vcc, 0, v7, vcc
	global_load_dword v30, v[18:19], off nt
	v_add_co_u32_e32 v18, vcc, s18, v6
	s_nop 1
	v_addc_co_u32_e32 v19, vcc, 0, v7, vcc
	global_load_dword v29, v[18:19], off nt
	v_add_co_u32_e32 v18, vcc, s19, v6
	s_nop 1
	v_addc_co_u32_e32 v19, vcc, 0, v7, vcc
	global_load_dword v28, v[18:19], off nt
	v_add_co_u32_e32 v18, vcc, s36, v6
	s_nop 1
	v_addc_co_u32_e32 v19, vcc, 0, v7, vcc
	global_load_dword v27, v[18:19], off nt
	v_add_co_u32_e32 v18, vcc, s37, v6
	s_nop 1
	v_addc_co_u32_e32 v19, vcc, 0, v7, vcc
	global_load_dword v26, v[18:19], off nt
	v_add_co_u32_e32 v18, vcc, s6, v6
	s_nop 1
	v_addc_co_u32_e32 v19, vcc, 0, v7, vcc
	global_load_dword v25, v[18:19], off nt
	v_add_co_u32_e32 v18, vcc, s7, v6
	s_nop 1
	v_addc_co_u32_e32 v19, vcc, 0, v7, vcc
	global_load_dword v24, v[18:19], off nt
	v_add_co_u32_e32 v18, vcc, s0, v6
	s_nop 1
	v_addc_co_u32_e32 v19, vcc, 0, v7, vcc
	global_load_dword v23, v[18:19], off nt
	v_add_co_u32_e32 v18, vcc, s1, v6
	s_nop 1
	v_addc_co_u32_e32 v19, vcc, 0, v7, vcc
	global_load_dword v22, v[18:19], off nt
	v_add_co_u32_e32 v18, vcc, s4, v6
	s_nop 1
	v_addc_co_u32_e32 v19, vcc, 0, v7, vcc
	global_load_dword v21, v[18:19], off nt
	v_add_co_u32_e32 v18, vcc, s5, v6
	s_nop 1
	v_addc_co_u32_e32 v19, vcc, 0, v7, vcc
	global_load_dword v20, v[18:19], off nt
	v_add_co_u32_e32 v18, vcc, s92, v6
	s_nop 1
	v_addc_co_u32_e32 v19, vcc, 0, v7, vcc
	v_add_co_u32_e32 v80, vcc, s93, v6
	global_load_dword v18, v[18:19], off nt
	s_nop 0
	v_addc_co_u32_e32 v81, vcc, 0, v7, vcc
	global_load_dword v17, v[80:81], off nt
	v_add_co_u32_e32 v80, vcc, s12, v6
	s_nop 1
	v_addc_co_u32_e32 v81, vcc, 0, v7, vcc
	global_load_dword v9, v[80:81], off nt
	v_add_co_u32_e32 v80, vcc, s13, v6
	s_nop 1
	v_addc_co_u32_e32 v81, vcc, 0, v7, vcc
	global_load_dword v0, v[80:81], off nt
	v_add_co_u32_e32 v80, vcc, s8, v6
	s_movk_i32 s8, 0x4000
	s_nop 0
	v_addc_co_u32_e32 v81, vcc, 0, v7, vcc
	global_load_dword v19, v[80:81], off nt
	s_waitcnt vmcnt(63)
	ds_write_b128 v13, v[100:103]
	ds_write_b128 v13, v[104:107] offset:8192
	ds_write_b128 v13, v[108:111] offset:16384
	ds_write_b128 v13, v[112:115] offset:24576
	s_waitcnt lgkmcnt(0)
	s_barrier
	ds_read2st64_b32 v[98:99], v11 offset1:1
	ds_read2st64_b32 v[100:101], v11 offset0:2 offset1:3
	ds_read2st64_b32 v[102:103], v11 offset0:4 offset1:5
	ds_read2st64_b32 v[104:105], v11 offset0:6 offset1:7
	ds_read2st64_b32 v[106:107], v11 offset0:8 offset1:9
	ds_read2st64_b32 v[108:109], v11 offset0:10 offset1:11
	ds_read2st64_b32 v[110:111], v11 offset0:12 offset1:13
	ds_read2st64_b32 v[112:113], v11 offset0:14 offset1:15
	ds_read2st64_b32 v[114:115], v11 offset0:16 offset1:17
	ds_read2st64_b32 v[116:117], v11 offset0:18 offset1:19
	ds_read2st64_b32 v[118:119], v11 offset0:20 offset1:21
	ds_read2st64_b32 v[120:121], v11 offset0:22 offset1:23
	ds_read2st64_b32 v[122:123], v11 offset0:24 offset1:25
	ds_read2st64_b32 v[124:125], v11 offset0:26 offset1:27
	ds_read2st64_b32 v[126:127], v11 offset0:28 offset1:29
	s_waitcnt lgkmcnt(0)
	ds_read2st64_b32 v[128:129], v11 offset0:30 offset1:31
	ds_read2st64_b32 v[130:131], v11 offset0:32 offset1:33
	ds_read2st64_b32 v[132:133], v11 offset0:34 offset1:35
	ds_read2st64_b32 v[134:135], v11 offset0:36 offset1:37
	ds_read2st64_b32 v[136:137], v11 offset0:38 offset1:39
	ds_read2st64_b32 v[138:139], v11 offset0:40 offset1:41
	ds_read2st64_b32 v[140:141], v11 offset0:42 offset1:43
	ds_read2st64_b32 v[142:143], v11 offset0:44 offset1:45
	ds_read2st64_b32 v[144:145], v11 offset0:46 offset1:47
	ds_read2st64_b32 v[146:147], v11 offset0:48 offset1:49
	ds_read2st64_b32 v[148:149], v11 offset0:50 offset1:51
	ds_read2st64_b32 v[150:151], v11 offset0:52 offset1:53
	ds_read2st64_b32 v[152:153], v11 offset0:54 offset1:55
	ds_read2st64_b32 v[154:155], v11 offset0:56 offset1:57
	ds_read2st64_b32 v[156:157], v11 offset0:58 offset1:59
	s_waitcnt lgkmcnt(0)
; DI bf16_t f2bf(float f) { return (bf16_t)(pk2(f, 0.f) & 0xffffu); }
; DI void gla_scan(const Params& p, int G, LAS unsigned char* lds) {
;     ...
; #pragma unroll
;             for (int j2 = 0; j2 < 64; ++j2) { sp[(size_t)(n0 + j2) * 8192] = f2bf(st); st = dl[(n0 + j2) * 64 + k] * st + dv[j2]; } }
	ds_read2st64_b32 v[158:159], v11 offset0:60 offset1:61
	ds_read2st64_b32 v[160:161], v11 offset0:62 offset1:63
	v_add_co_u32_e32 v82, vcc, s8, v4
	s_mov_b32 s8, 0xc000
	s_nop 0
	v_addc_co_u32_e32 v83, vcc, 0, v5, vcc
	s_waitcnt vmcnt(62) lgkmcnt(0)
	v_fmac_f32_e32 v78, 0, v98
	v_cvt_pk_bf16_f32 v8, v78, s0
	v_fmac_f32_e32 v77, v78, v99
	v_add_co_u32_e32 v78, vcc, s38, v4
	global_store_short v[82:83], v8, off
	v_cvt_pk_bf16_f32 v8, v77, s0
	v_addc_co_u32_e32 v79, vcc, 0, v5, vcc
	global_store_short v[78:79], v8, off
	v_add_co_u32_e32 v80, vcc, s8, v4
	s_mov_b32 s8, 0x14000
	s_nop 0
	v_addc_co_u32_e32 v81, vcc, 0, v5, vcc
	s_waitcnt lgkmcnt(0)
	v_fmac_f32_e32 v76, v77, v100
	v_cvt_pk_bf16_f32 v8, v76, s0
	s_waitcnt vmcnt(62)
	v_fmac_f32_e32 v75, v76, v101
	v_add_co_u32_e32 v76, vcc, s39, v4
	global_store_short v[80:81], v8, off
	v_cvt_pk_bf16_f32 v8, v75, s0
	v_addc_co_u32_e32 v77, vcc, 0, v5, vcc
	global_store_short v[76:77], v8, off
	v_add_co_u32_e32 v78, vcc, s8, v4
	s_mov_b32 s8, 0x1c000
	s_nop 0
	v_addc_co_u32_e32 v79, vcc, 0, v5, vcc
	s_waitcnt vmcnt(62) lgkmcnt(0)
	v_fmac_f32_e32 v74, v75, v102
	v_cvt_pk_bf16_f32 v8, v74, s0
	v_fmac_f32_e32 v73, v74, v103
	v_add_co_u32_e32 v74, vcc, s40, v4
	global_store_short v[78:79], v8, off
	v_cvt_pk_bf16_f32 v8, v73, s0
	v_addc_co_u32_e32 v75, vcc, 0, v5, vcc
	global_store_short v[74:75], v8, off
	v_add_co_u32_e32 v76, vcc, s8, v4
	s_mov_b32 s8, 0x24000
	s_nop 0
	v_addc_co_u32_e32 v77, vcc, 0, v5, vcc
	s_waitcnt vmcnt(62) lgkmcnt(0)
	v_fmac_f32_e32 v72, v73, v104
	v_cvt_pk_bf16_f32 v8, v72, s0
	v_fmac_f32_e32 v71, v72, v105
	v_add_co_u32_e32 v72, vcc, s41, v4
	global_store_short v[76:77], v8, off
	v_cvt_pk_bf16_f32 v8, v71, s0
	v_addc_co_u32_e32 v73, vcc, 0, v5, vcc
	global_store_short v[72:73], v8, off
	v_add_co_u32_e32 v74, vcc, s8, v4
	s_mov_b32 s8, 0x2c000
	s_nop 0
	v_addc_co_u32_e32 v75, vcc, 0, v5, vcc
	s_waitcnt vmcnt(62) lgkmcnt(0)
	v_fmac_f32_e32 v70, v71, v106
	v_cvt_pk_bf16_f32 v8, v70, s0
	v_fmac_f32_e32 v69, v70, v107
	v_add_co_u32_e32 v70, vcc, s42, v4
	global_store_short v[74:75], v8, off
	v_cvt_pk_bf16_f32 v8, v69, s0
	v_addc_co_u32_e32 v71, vcc, 0, v5, vcc
	global_store_short v[70:71], v8, off
	v_add_co_u32_e32 v72, vcc, s8, v4
	s_mov_b32 s8, 0x34000
	s_nop 0
	v_addc_co_u32_e32 v73, vcc, 0, v5, vcc
	s_waitcnt vmcnt(62) lgkmcnt(0)
	v_fmac_f32_e32 v68, v69, v108
	v_cvt_pk_bf16_f32 v8, v68, s0
	v_fmac_f32_e32 v67, v68, v109
	v_add_co_u32_e32 v68, vcc, s43, v4
	global_store_short v[72:73], v8, off
	v_cvt_pk_bf16_f32 v8, v67, s0
	v_addc_co_u32_e32 v69, vcc, 0, v5, vcc
	global_store_short v[68:69], v8, off
	v_add_co_u32_e32 v70, vcc, s8, v4
	s_mov_b32 s8, 0x3c000
	s_nop 0
	v_addc_co_u32_e32 v71, vcc, 0, v5, vcc
	s_waitcnt vmcnt(62) lgkmcnt(0)
	v_fmac_f32_e32 v66, v67, v110
	v_cvt_pk_bf16_f32 v8, v66, s0
	v_fmac_f32_e32 v65, v66, v111
	v_add_co_u32_e32 v66, vcc, s44, v4
	global_store_short v[70:71], v8, off
	v_cvt_pk_bf16_f32 v8, v65, s0
	v_addc_co_u32_e32 v67, vcc, 0, v5, vcc
	global_store_short v[66:67], v8, off
	v_add_co_u32_e32 v68, vcc, s8, v4
	s_mov_b32 s8, 0x44000
	s_nop 0
	v_addc_co_u32_e32 v69, vcc, 0, v5, vcc
	s_waitcnt vmcnt(62) lgkmcnt(0)
	v_fmac_f32_e32 v64, v65, v112
	v_cvt_pk_bf16_f32 v8, v64, s0
	v_fmac_f32_e32 v63, v64, v113
	v_add_co_u32_e32 v64, vcc, s45, v4
	global_store_short v[68:69], v8, off
	v_cvt_pk_bf16_f32 v8, v63, s0
	v_addc_co_u32_e32 v65, vcc, 0, v5, vcc
	global_store_short v[64:65], v8, off
	v_add_co_u32_e32 v66, vcc, s8, v4
	s_mov_b32 s8, 0x4c000
	s_nop 0
	v_addc_co_u32_e32 v67, vcc, 0, v5, vcc
	s_waitcnt vmcnt(62) lgkmcnt(0)
	v_fmac_f32_e32 v62, v63, v114
	v_cvt_pk_bf16_f32 v8, v62, s0
	v_fmac_f32_e32 v61, v62, v115
	v_add_co_u32_e32 v62, vcc, s46, v4
	global_store_short v[66:67], v8, off
	v_cvt_pk_bf16_f32 v8, v61, s0
	v_addc_co_u32_e32 v63, vcc, 0, v5, vcc
	global_store_short v[62:63], v8, off
	v_add_co_u32_e32 v64, vcc, s8, v4
	s_mov_b32 s8, 0x54000
	s_nop 0
	v_addc_co_u32_e32 v65, vcc, 0, v5, vcc
	s_waitcnt vmcnt(62) lgkmcnt(0)
	v_fmac_f32_e32 v60, v61, v116
	v_cvt_pk_bf16_f32 v8, v60, s0
	v_fmac_f32_e32 v59, v60, v117
	v_add_co_u32_e32 v60, vcc, s47, v4
	global_store_short v[64:65], v8, off
	v_cvt_pk_bf16_f32 v8, v59, s0
	v_addc_co_u32_e32 v61, vcc, 0, v5, vcc
	global_store_short v[60:61], v8, off
	v_add_co_u32_e32 v62, vcc, s8, v4
	s_mov_b32 s8, 0x5c000
	s_nop 0
	v_addc_co_u32_e32 v63, vcc, 0, v5, vcc
	s_waitcnt vmcnt(62) lgkmcnt(0)
	v_fmac_f32_e32 v58, v59, v118
	v_cvt_pk_bf16_f32 v8, v58, s0
	v_fmac_f32_e32 v57, v58, v119
	v_add_co_u32_e32 v58, vcc, s48, v4
	global_store_short v[62:63], v8, off
	v_cvt_pk_bf16_f32 v8, v57, s0
	v_addc_co_u32_e32 v59, vcc, 0, v5, vcc
	global_store_short v[58:59], v8, off
	v_add_co_u32_e32 v60, vcc, s8, v4
	s_mov_b32 s8, 0x64000
	s_nop 0
	v_addc_co_u32_e32 v61, vcc, 0, v5, vcc
	s_waitcnt vmcnt(62) lgkmcnt(0)
	v_fmac_f32_e32 v56, v57, v120
	v_cvt_pk_bf16_f32 v8, v56, s0
	v_fmac_f32_e32 v55, v56, v121
	v_add_co_u32_e32 v56, vcc, s49, v4
	global_store_short v[60:61], v8, off
	v_cvt_pk_bf16_f32 v8, v55, s0
	v_addc_co_u32_e32 v57, vcc, 0, v5, vcc
	global_store_short v[56:57], v8, off
	v_add_co_u32_e32 v58, vcc, s8, v4
	s_mov_b32 s8, 0x6c000
	s_nop 0
	v_addc_co_u32_e32 v59, vcc, 0, v5, vcc
	s_waitcnt vmcnt(62) lgkmcnt(0)
	v_fmac_f32_e32 v54, v55, v122
	v_cvt_pk_bf16_f32 v8, v54, s0
	v_fmac_f32_e32 v53, v54, v123
	v_add_co_u32_e32 v54, vcc, s50, v4
	global_store_short v[58:59], v8, off
	v_cvt_pk_bf16_f32 v8, v53, s0
	v_addc_co_u32_e32 v55, vcc, 0, v5, vcc
	global_store_short v[54:55], v8, off
	v_add_co_u32_e32 v56, vcc, s8, v4
	s_mov_b32 s8, 0x74000
	s_nop 0
	v_addc_co_u32_e32 v57, vcc, 0, v5, vcc
	s_waitcnt vmcnt(62) lgkmcnt(0)
; DI bf16_t f2bf(float f) { return (bf16_t)(pk2(f, 0.f) & 0xffffu); }
; DI void gla_scan(const Params& p, int G, LAS unsigned char* lds) {
;     ...
; #pragma unroll
;             for (int j2 = 0; j2 < 64; ++j2) { sp[(size_t)(n0 + j2) * 8192] = f2bf(st); st = dl[(n0 + j2) * 64 + k] * st + dv[j2]; } }
	v_fmac_f32_e32 v52, v53, v124
	v_cvt_pk_bf16_f32 v8, v52, s0
	v_fmac_f32_e32 v51, v52, v125
	v_add_co_u32_e32 v52, vcc, s51, v4
	global_store_short v[56:57], v8, off
	v_cvt_pk_bf16_f32 v8, v51, s0
	v_addc_co_u32_e32 v53, vcc, 0, v5, vcc
	global_store_short v[52:53], v8, off
	v_add_co_u32_e32 v54, vcc, s8, v4
	s_mov_b32 s8, 0x7c000
	s_nop 0
	v_addc_co_u32_e32 v55, vcc, 0, v5, vcc
	s_waitcnt vmcnt(62) lgkmcnt(0)
	v_fmac_f32_e32 v50, v51, v126
	v_cvt_pk_bf16_f32 v8, v50, s0
	v_fmac_f32_e32 v49, v50, v127
	v_add_co_u32_e32 v50, vcc, s52, v4
	global_store_short v[54:55], v8, off
	v_cvt_pk_bf16_f32 v8, v49, s0
	v_addc_co_u32_e32 v51, vcc, 0, v5, vcc
	global_store_short v[50:51], v8, off
	v_add_co_u32_e32 v52, vcc, s8, v4
	s_mov_b32 s8, 0x84000
	s_nop 0
	v_addc_co_u32_e32 v53, vcc, 0, v5, vcc
	s_waitcnt vmcnt(62) lgkmcnt(0)
	v_fmac_f32_e32 v48, v49, v128
	v_cvt_pk_bf16_f32 v8, v48, s0
	v_fmac_f32_e32 v47, v48, v129
	v_add_co_u32_e32 v48, vcc, s53, v4
	global_store_short v[52:53], v8, off
	v_cvt_pk_bf16_f32 v8, v47, s0
	v_addc_co_u32_e32 v49, vcc, 0, v5, vcc
	global_store_short v[48:49], v8, off
	v_add_co_u32_e32 v50, vcc, s8, v4
	s_mov_b32 s8, 0x8c000
	s_nop 0
	v_addc_co_u32_e32 v51, vcc, 0, v5, vcc
	s_waitcnt vmcnt(62) lgkmcnt(0)
	v_fmac_f32_e32 v46, v47, v130
	v_cvt_pk_bf16_f32 v8, v46, s0
	v_fmac_f32_e32 v45, v46, v131
	v_add_co_u32_e32 v46, vcc, s55, v4
	global_store_short v[50:51], v8, off
	v_cvt_pk_bf16_f32 v8, v45, s0
	v_addc_co_u32_e32 v47, vcc, 0, v5, vcc
	global_store_short v[46:47], v8, off
	v_add_co_u32_e32 v48, vcc, s8, v4
	s_mov_b32 s8, 0x94000
	s_nop 0
	v_addc_co_u32_e32 v49, vcc, 0, v5, vcc
	s_waitcnt vmcnt(62) lgkmcnt(0)
	v_fmac_f32_e32 v44, v45, v132
	v_cvt_pk_bf16_f32 v8, v44, s0
	v_fmac_f32_e32 v43, v44, v133
	v_add_co_u32_e32 v44, vcc, s56, v4
	global_store_short v[48:49], v8, off
	v_cvt_pk_bf16_f32 v8, v43, s0
	v_addc_co_u32_e32 v45, vcc, 0, v5, vcc
	global_store_short v[44:45], v8, off
	v_add_co_u32_e32 v46, vcc, s8, v4
	s_mov_b32 s8, 0x9c000
	s_nop 0
	v_addc_co_u32_e32 v47, vcc, 0, v5, vcc
	s_waitcnt vmcnt(62) lgkmcnt(0)
	v_fmac_f32_e32 v42, v43, v134
	v_cvt_pk_bf16_f32 v8, v42, s0
	v_fmac_f32_e32 v41, v42, v135
	v_add_co_u32_e32 v42, vcc, s57, v4
	global_store_short v[46:47], v8, off
	v_cvt_pk_bf16_f32 v8, v41, s0
	v_addc_co_u32_e32 v43, vcc, 0, v5, vcc
	global_store_short v[42:43], v8, off
	v_add_co_u32_e32 v44, vcc, s8, v4
	s_mov_b32 s8, 0xa4000
	s_nop 0
	v_addc_co_u32_e32 v45, vcc, 0, v5, vcc
	s_waitcnt vmcnt(62) lgkmcnt(0)
	v_fmac_f32_e32 v40, v41, v136
	v_cvt_pk_bf16_f32 v8, v40, s0
	v_fmac_f32_e32 v39, v40, v137
	v_add_co_u32_e32 v40, vcc, s58, v4
	global_store_short v[44:45], v8, off
	v_cvt_pk_bf16_f32 v8, v39, s0
	v_addc_co_u32_e32 v41, vcc, 0, v5, vcc
	global_store_short v[40:41], v8, off
	v_add_co_u32_e32 v42, vcc, s8, v4
	s_mov_b32 s8, 0xac000
	s_nop 0
	v_addc_co_u32_e32 v43, vcc, 0, v5, vcc
	s_waitcnt vmcnt(62) lgkmcnt(0)
	v_fmac_f32_e32 v38, v39, v138
	v_cvt_pk_bf16_f32 v8, v38, s0
	v_fmac_f32_e32 v37, v38, v139
	v_add_co_u32_e32 v38, vcc, s59, v4
	global_store_short v[42:43], v8, off
	v_cvt_pk_bf16_f32 v8, v37, s0
	v_addc_co_u32_e32 v39, vcc, 0, v5, vcc
	global_store_short v[38:39], v8, off
	v_add_co_u32_e32 v40, vcc, s8, v4
	s_mov_b32 s8, 0xb4000
	s_nop 0
	v_addc_co_u32_e32 v41, vcc, 0, v5, vcc
	s_waitcnt vmcnt(62) lgkmcnt(0)
	v_fmac_f32_e32 v36, v37, v140
	v_cvt_pk_bf16_f32 v8, v36, s0
	v_fmac_f32_e32 v35, v36, v141
	v_add_co_u32_e32 v36, vcc, s60, v4
	global_store_short v[40:41], v8, off
	v_cvt_pk_bf16_f32 v8, v35, s0
	v_addc_co_u32_e32 v37, vcc, 0, v5, vcc
	global_store_short v[36:37], v8, off
	v_add_co_u32_e32 v38, vcc, s8, v4
	s_mov_b32 s8, 0xbc000
	s_nop 0
	v_addc_co_u32_e32 v39, vcc, 0, v5, vcc
	s_waitcnt vmcnt(62) lgkmcnt(0)
	v_fmac_f32_e32 v34, v35, v142
	v_cvt_pk_bf16_f32 v8, v34, s0
	v_fmac_f32_e32 v33, v34, v143
	v_add_co_u32_e32 v34, vcc, s61, v4
	global_store_short v[38:39], v8, off
	v_cvt_pk_bf16_f32 v8, v33, s0
	v_addc_co_u32_e32 v35, vcc, 0, v5, vcc
	global_store_short v[34:35], v8, off
	v_add_co_u32_e32 v36, vcc, s8, v4
	s_mov_b32 s8, 0xc4000
	s_nop 0
	v_addc_co_u32_e32 v37, vcc, 0, v5, vcc
	s_waitcnt vmcnt(62) lgkmcnt(0)
	v_fmac_f32_e32 v32, v33, v144
	v_cvt_pk_bf16_f32 v8, v32, s0
	v_fmac_f32_e32 v31, v32, v145
	v_add_co_u32_e32 v32, vcc, s62, v4
	global_store_short v[36:37], v8, off
	v_cvt_pk_bf16_f32 v8, v31, s0
	v_addc_co_u32_e32 v33, vcc, 0, v5, vcc
	global_store_short v[32:33], v8, off
	v_add_co_u32_e32 v34, vcc, s8, v4
	s_mov_b32 s8, 0xcc000
	s_nop 0
	v_addc_co_u32_e32 v35, vcc, 0, v5, vcc
	s_waitcnt vmcnt(62) lgkmcnt(0)
	v_fmac_f32_e32 v30, v31, v146
	v_cvt_pk_bf16_f32 v8, v30, s0
	v_fmac_f32_e32 v29, v30, v147
	v_add_co_u32_e32 v30, vcc, s63, v4
	global_store_short v[34:35], v8, off
	v_cvt_pk_bf16_f32 v8, v29, s0
	v_addc_co_u32_e32 v31, vcc, 0, v5, vcc
	global_store_short v[30:31], v8, off
	v_add_co_u32_e32 v32, vcc, s8, v4
	s_mov_b32 s8, 0xd4000
	s_nop 0
	v_addc_co_u32_e32 v33, vcc, 0, v5, vcc
	s_waitcnt vmcnt(62) lgkmcnt(0)
	v_fmac_f32_e32 v28, v29, v148
	v_cvt_pk_bf16_f32 v8, v28, s0
	v_fmac_f32_e32 v27, v28, v149
	v_add_co_u32_e32 v28, vcc, s64, v4
	global_store_short v[32:33], v8, off
	v_cvt_pk_bf16_f32 v8, v27, s0
	v_addc_co_u32_e32 v29, vcc, 0, v5, vcc
	global_store_short v[28:29], v8, off
	v_add_co_u32_e32 v30, vcc, s8, v4
	s_mov_b32 s8, 0xdc000
	s_nop 0
	v_addc_co_u32_e32 v31, vcc, 0, v5, vcc
	s_waitcnt vmcnt(62) lgkmcnt(0)
	v_fmac_f32_e32 v26, v27, v150
	v_cvt_pk_bf16_f32 v8, v26, s0
	v_fmac_f32_e32 v25, v26, v151
	v_add_co_u32_e32 v26, vcc, s65, v4
	global_store_short v[30:31], v8, off
	v_cvt_pk_bf16_f32 v8, v25, s0
	v_addc_co_u32_e32 v27, vcc, 0, v5, vcc
	global_store_short v[26:27], v8, off
	v_add_co_u32_e32 v28, vcc, s8, v4
	s_mov_b32 s8, 0xe4000
	s_nop 0
	v_addc_co_u32_e32 v29, vcc, 0, v5, vcc
	s_waitcnt vmcnt(62) lgkmcnt(0)
; DI bf16_t f2bf(float f) { return (bf16_t)(pk2(f, 0.f) & 0xffffu); }
; DI void gla_scan(const Params& p, int G, LAS unsigned char* lds) {
;     ...
;         for (int n0 = 0; n0 < 128; n0 += 64) { float dv[64];
; #pragma unroll
;             for (int j2 = 0; j2 < 64; ++j2) dv[j2] = __builtin_nontemporal_load(dp + (size_t)(n0 + j2) * 8192);
; #pragma unroll
;             for (int j2 = 0; j2 < 64; ++j2) { sp[(size_t)(n0 + j2) * 8192] = f2bf(st); st = dl[(n0 + j2) * 64 + k] * st + dv[j2]; } }
	v_fmac_f32_e32 v24, v25, v152
	v_cvt_pk_bf16_f32 v8, v24, s0
	v_fmac_f32_e32 v23, v24, v153
	v_add_co_u32_e32 v24, vcc, s66, v4
	global_store_short v[28:29], v8, off
	v_cvt_pk_bf16_f32 v8, v23, s0
	v_addc_co_u32_e32 v25, vcc, 0, v5, vcc
	global_store_short v[24:25], v8, off
	v_add_co_u32_e32 v26, vcc, s8, v4
	s_mov_b32 s8, 0xec000
	s_nop 0
	v_addc_co_u32_e32 v27, vcc, 0, v5, vcc
	s_waitcnt vmcnt(62) lgkmcnt(0)
	v_fmac_f32_e32 v22, v23, v154
	v_cvt_pk_bf16_f32 v8, v22, s0
	v_fmac_f32_e32 v21, v22, v155
	v_add_co_u32_e32 v22, vcc, s67, v4
	global_store_short v[26:27], v8, off
	v_cvt_pk_bf16_f32 v8, v21, s0
	v_addc_co_u32_e32 v23, vcc, 0, v5, vcc
	global_store_short v[22:23], v8, off
	v_add_co_u32_e32 v24, vcc, s8, v4
	s_mov_b32 s8, 0xf4000
	s_nop 0
	v_addc_co_u32_e32 v25, vcc, 0, v5, vcc
	s_waitcnt vmcnt(62) lgkmcnt(0)
	v_fmac_f32_e32 v20, v21, v156
	v_cvt_pk_bf16_f32 v8, v20, s0
	v_fmac_f32_e32 v18, v20, v157
	v_add_co_u32_e32 v20, vcc, s68, v4
	global_store_short v[24:25], v8, off
	v_cvt_pk_bf16_f32 v8, v18, s0
	v_addc_co_u32_e32 v21, vcc, 0, v5, vcc
	global_store_short v[20:21], v8, off
	v_add_co_u32_e32 v22, vcc, s8, v4
	s_mov_b32 s8, 0xfc000
	s_nop 0
	v_addc_co_u32_e32 v23, vcc, 0, v5, vcc
	s_waitcnt vmcnt(62) lgkmcnt(0)
	v_fmac_f32_e32 v17, v18, v158
	v_cvt_pk_bf16_f32 v8, v17, s0
	v_fmac_f32_e32 v9, v17, v159
	v_add_co_u32_e32 v20, vcc, s69, v4
	global_store_short v[22:23], v8, off
	v_cvt_pk_bf16_f32 v8, v9, s0
	v_addc_co_u32_e32 v21, vcc, 0, v5, vcc
	global_store_short v[20:21], v8, off
	v_add_co_u32_e32 v8, vcc, s8, v4
	s_mov_b32 s8, 0x200000
	s_waitcnt vmcnt(62) lgkmcnt(0)
	v_fmac_f32_e32 v0, v9, v160
	v_cvt_pk_bf16_f32 v17, v0, s0
	v_addc_co_u32_e32 v9, vcc, 0, v5, vcc
	global_store_short v[8:9], v17, off
	v_add_co_u32_e32 v8, vcc, s8, v6
	s_mov_b32 s8, 0x208000
	s_nop 0
	v_addc_co_u32_e32 v9, vcc, 0, v7, vcc
	v_fmac_f32_e32 v19, v0, v161
	ds_read2st64_b32 v[98:99], v11 offset0:64 offset1:65
	ds_read2st64_b32 v[100:101], v11 offset0:66 offset1:67
	ds_read2st64_b32 v[102:103], v11 offset0:68 offset1:69
	ds_read2st64_b32 v[104:105], v11 offset0:70 offset1:71
	ds_read2st64_b32 v[106:107], v11 offset0:72 offset1:73
	ds_read2st64_b32 v[108:109], v11 offset0:74 offset1:75
	ds_read2st64_b32 v[110:111], v11 offset0:76 offset1:77
	ds_read2st64_b32 v[112:113], v11 offset0:78 offset1:79
	ds_read2st64_b32 v[114:115], v11 offset0:80 offset1:81
	ds_read2st64_b32 v[116:117], v11 offset0:82 offset1:83
	ds_read2st64_b32 v[118:119], v11 offset0:84 offset1:85
	ds_read2st64_b32 v[120:121], v11 offset0:86 offset1:87
	ds_read2st64_b32 v[122:123], v11 offset0:88 offset1:89
	ds_read2st64_b32 v[124:125], v11 offset0:90 offset1:91
	ds_read2st64_b32 v[126:127], v11 offset0:92 offset1:93
	s_waitcnt lgkmcnt(0)
	ds_read2st64_b32 v[128:129], v11 offset0:94 offset1:95
	ds_read2st64_b32 v[130:131], v11 offset0:96 offset1:97
	ds_read2st64_b32 v[132:133], v11 offset0:98 offset1:99
	ds_read2st64_b32 v[134:135], v11 offset0:100 offset1:101
	ds_read2st64_b32 v[136:137], v11 offset0:102 offset1:103
	ds_read2st64_b32 v[138:139], v11 offset0:104 offset1:105
	ds_read2st64_b32 v[140:141], v11 offset0:106 offset1:107
	ds_read2st64_b32 v[142:143], v11 offset0:108 offset1:109
	ds_read2st64_b32 v[144:145], v11 offset0:110 offset1:111
	ds_read2st64_b32 v[146:147], v11 offset0:112 offset1:113
	ds_read2st64_b32 v[148:149], v11 offset0:114 offset1:115
	ds_read2st64_b32 v[150:151], v11 offset0:116 offset1:117
	ds_read2st64_b32 v[152:153], v11 offset0:118 offset1:119
	ds_read2st64_b32 v[154:155], v11 offset0:120 offset1:121
	ds_read2st64_b32 v[156:157], v11 offset0:122 offset1:123
	s_waitcnt lgkmcnt(0)
	ds_read2st64_b32 v[158:159], v11 offset0:124 offset1:125
	ds_read_b32 v160, v11 offset:32256
	global_load_dword v0, v[8:9], off nt
	v_add_co_u32_e32 v8, vcc, s8, v6
	s_mov_b32 s8, 0x210000
	s_nop 0
	v_addc_co_u32_e32 v9, vcc, 0, v7, vcc
	global_load_dword v77, v[8:9], off nt
	v_add_co_u32_e32 v8, vcc, s8, v6
	s_mov_b32 s8, 0x218000
	s_nop 0
	v_addc_co_u32_e32 v9, vcc, 0, v7, vcc
	global_load_dword v75, v[8:9], off nt
	v_add_co_u32_e32 v8, vcc, s8, v6
	s_mov_b32 s8, 0x220000
	s_nop 0
	v_addc_co_u32_e32 v9, vcc, 0, v7, vcc
	global_load_dword v76, v[8:9], off nt
	v_add_co_u32_e32 v8, vcc, s8, v6
	s_mov_b32 s8, 0x228000
	s_nop 0
	v_addc_co_u32_e32 v9, vcc, 0, v7, vcc
	global_load_dword v73, v[8:9], off nt
	v_add_co_u32_e32 v8, vcc, s8, v6
	s_mov_b32 s8, 0x230000
	s_nop 0
	v_addc_co_u32_e32 v9, vcc, 0, v7, vcc
	global_load_dword v74, v[8:9], off nt
	v_add_co_u32_e32 v8, vcc, s8, v6
	s_mov_b32 s8, 0x238000
	s_nop 0
	v_addc_co_u32_e32 v9, vcc, 0, v7, vcc
	global_load_dword v71, v[8:9], off nt
	v_add_co_u32_e32 v8, vcc, s8, v6
	s_mov_b32 s8, 0x240000
	s_nop 0
	v_addc_co_u32_e32 v9, vcc, 0, v7, vcc
	global_load_dword v72, v[8:9], off nt
	v_add_co_u32_e32 v8, vcc, s8, v6
	s_mov_b32 s8, 0x248000
	s_nop 0
	v_addc_co_u32_e32 v9, vcc, 0, v7, vcc
	global_load_dword v68, v[8:9], off nt
	v_add_co_u32_e32 v8, vcc, s8, v6
	s_mov_b32 s8, 0x250000
	s_nop 0
	v_addc_co_u32_e32 v9, vcc, 0, v7, vcc
	global_load_dword v69, v[8:9], off nt
	v_add_co_u32_e32 v8, vcc, s8, v6
	s_mov_b32 s8, 0x258000
	s_nop 0
	v_addc_co_u32_e32 v9, vcc, 0, v7, vcc
	global_load_dword v62, v[8:9], off nt
	v_add_co_u32_e32 v8, vcc, s8, v6
	s_mov_b32 s8, 0x260000
	s_nop 0
	v_addc_co_u32_e32 v9, vcc, 0, v7, vcc
	global_load_dword v63, v[8:9], off nt
	v_add_co_u32_e32 v8, vcc, s8, v6
	s_mov_b32 s8, 0x268000
	s_nop 0
	v_addc_co_u32_e32 v9, vcc, 0, v7, vcc
	global_load_dword v59, v[8:9], off nt
	v_add_co_u32_e32 v8, vcc, s8, v6
	s_mov_b32 s8, 0x270000
	s_nop 0
	v_addc_co_u32_e32 v9, vcc, 0, v7, vcc
	global_load_dword v70, v[8:9], off nt
; DI void gla_scan(const Params& p, int G, LAS unsigned char* lds) {
;     ...
;         for (int n0 = 0; n0 < 128; n0 += 64) { float dv[64];
; #pragma unroll
;             for (int j2 = 0; j2 < 64; ++j2) dv[j2] = __builtin_nontemporal_load(dp + (size_t)(n0 + j2) * 8192);
	v_add_co_u32_e32 v8, vcc, s8, v6
	s_mov_b32 s8, 0x278000
	s_nop 0
	v_addc_co_u32_e32 v9, vcc, 0, v7, vcc
	global_load_dword v66, v[8:9], off nt
	v_add_co_u32_e32 v8, vcc, s8, v6
	s_mov_b32 s8, 0x280000
	s_nop 0
	v_addc_co_u32_e32 v9, vcc, 0, v7, vcc
	global_load_dword v67, v[8:9], off nt
	v_add_co_u32_e32 v8, vcc, s8, v6
	s_mov_b32 s8, 0x288000
	s_nop 0
	v_addc_co_u32_e32 v9, vcc, 0, v7, vcc
	global_load_dword v64, v[8:9], off nt
	v_add_co_u32_e32 v8, vcc, s8, v6
	s_mov_b32 s8, 0x290000
	s_nop 0
	v_addc_co_u32_e32 v9, vcc, 0, v7, vcc
	global_load_dword v65, v[8:9], off nt
	v_add_co_u32_e32 v8, vcc, s8, v6
	s_mov_b32 s8, 0x298000
	s_nop 0
	v_addc_co_u32_e32 v9, vcc, 0, v7, vcc
	global_load_dword v60, v[8:9], off nt
	v_add_co_u32_e32 v8, vcc, s8, v6
	s_mov_b32 s8, 0x2a0000
	s_nop 0
	v_addc_co_u32_e32 v9, vcc, 0, v7, vcc
	global_load_dword v61, v[8:9], off nt
	v_add_co_u32_e32 v8, vcc, s8, v6
	s_mov_b32 s8, 0x2a8000
	s_nop 0
	v_addc_co_u32_e32 v9, vcc, 0, v7, vcc
	global_load_dword v57, v[8:9], off nt
	v_add_co_u32_e32 v8, vcc, s8, v6
	s_mov_b32 s8, 0x2b0000
	s_nop 0
	v_addc_co_u32_e32 v9, vcc, 0, v7, vcc
	global_load_dword v58, v[8:9], off nt
	v_add_co_u32_e32 v8, vcc, s8, v6
	s_mov_b32 s8, 0x2b8000
	s_nop 0
	v_addc_co_u32_e32 v9, vcc, 0, v7, vcc
	global_load_dword v55, v[8:9], off nt
	v_add_co_u32_e32 v8, vcc, s8, v6
	s_mov_b32 s8, 0x2c0000
	s_nop 0
	v_addc_co_u32_e32 v9, vcc, 0, v7, vcc
	global_load_dword v56, v[8:9], off nt
	v_add_co_u32_e32 v8, vcc, s8, v6
	s_mov_b32 s8, 0x2c8000
	s_nop 0
	v_addc_co_u32_e32 v9, vcc, 0, v7, vcc
	global_load_dword v53, v[8:9], off nt
	v_add_co_u32_e32 v8, vcc, s8, v6
	s_mov_b32 s8, 0x2d0000
	s_nop 0
	v_addc_co_u32_e32 v9, vcc, 0, v7, vcc
	global_load_dword v54, v[8:9], off nt
	v_add_co_u32_e32 v8, vcc, s8, v6
	s_mov_b32 s8, 0x2d8000
	s_nop 0
	v_addc_co_u32_e32 v9, vcc, 0, v7, vcc
	global_load_dword v51, v[8:9], off nt
	v_add_co_u32_e32 v8, vcc, s8, v6
	s_mov_b32 s8, 0x2e0000
	s_nop 0
	v_addc_co_u32_e32 v9, vcc, 0, v7, vcc
	global_load_dword v52, v[8:9], off nt
	v_add_co_u32_e32 v8, vcc, s8, v6
	s_mov_b32 s8, 0x2e8000
	s_nop 0
	v_addc_co_u32_e32 v9, vcc, 0, v7, vcc
	global_load_dword v49, v[8:9], off nt
	v_add_co_u32_e32 v8, vcc, s8, v6
	s_mov_b32 s8, 0x2f0000
	s_nop 0
	v_addc_co_u32_e32 v9, vcc, 0, v7, vcc
	global_load_dword v50, v[8:9], off nt
	v_add_co_u32_e32 v8, vcc, s8, v6
	s_mov_b32 s8, 0x2f8000
	s_nop 0
	v_addc_co_u32_e32 v9, vcc, 0, v7, vcc
	global_load_dword v47, v[8:9], off nt
	v_add_co_u32_e32 v8, vcc, s8, v6
	s_mov_b32 s8, 0x300000
	s_nop 0
	v_addc_co_u32_e32 v9, vcc, 0, v7, vcc
	global_load_dword v48, v[8:9], off nt
	v_add_co_u32_e32 v8, vcc, s8, v6
	s_mov_b32 s8, 0x308000
	s_nop 0
	v_addc_co_u32_e32 v9, vcc, 0, v7, vcc
	global_load_dword v45, v[8:9], off nt
	v_add_co_u32_e32 v8, vcc, s8, v6
	s_mov_b32 s8, 0x310000
	s_nop 0
	v_addc_co_u32_e32 v9, vcc, 0, v7, vcc
	global_load_dword v46, v[8:9], off nt
	v_add_co_u32_e32 v8, vcc, s8, v6
	s_mov_b32 s8, 0x318000
	s_nop 0
	v_addc_co_u32_e32 v9, vcc, 0, v7, vcc
	global_load_dword v43, v[8:9], off nt
	v_add_co_u32_e32 v8, vcc, s8, v6
	s_mov_b32 s8, 0x320000
	s_nop 0
	v_addc_co_u32_e32 v9, vcc, 0, v7, vcc
	global_load_dword v44, v[8:9], off nt
	v_add_co_u32_e32 v8, vcc, s8, v6
	s_mov_b32 s8, 0x328000
	s_nop 0
	v_addc_co_u32_e32 v9, vcc, 0, v7, vcc
	global_load_dword v41, v[8:9], off nt
	v_add_co_u32_e32 v8, vcc, s8, v6
	s_mov_b32 s8, 0x330000
	s_nop 0
	v_addc_co_u32_e32 v9, vcc, 0, v7, vcc
	global_load_dword v42, v[8:9], off nt
	v_add_co_u32_e32 v8, vcc, s8, v6
	s_mov_b32 s8, 0x338000
	s_nop 0
	v_addc_co_u32_e32 v9, vcc, 0, v7, vcc
	global_load_dword v39, v[8:9], off nt
	v_add_co_u32_e32 v8, vcc, s8, v6
	s_mov_b32 s8, 0x340000
	s_nop 0
	v_addc_co_u32_e32 v9, vcc, 0, v7, vcc
	global_load_dword v40, v[8:9], off nt
	v_add_co_u32_e32 v8, vcc, s8, v6
	s_mov_b32 s8, 0x348000
	s_nop 0
	v_addc_co_u32_e32 v9, vcc, 0, v7, vcc
	global_load_dword v37, v[8:9], off nt
	v_add_co_u32_e32 v8, vcc, s8, v6
	s_mov_b32 s8, 0x350000
	s_nop 0
	v_addc_co_u32_e32 v9, vcc, 0, v7, vcc
	global_load_dword v38, v[8:9], off nt
	v_add_co_u32_e32 v8, vcc, s8, v6
	s_mov_b32 s8, 0x358000
	s_nop 0
	v_addc_co_u32_e32 v9, vcc, 0, v7, vcc
	global_load_dword v35, v[8:9], off nt
	v_add_co_u32_e32 v8, vcc, s8, v6
	s_mov_b32 s8, 0x360000
	s_nop 0
	v_addc_co_u32_e32 v9, vcc, 0, v7, vcc
	global_load_dword v36, v[8:9], off nt
	v_add_co_u32_e32 v8, vcc, s8, v6
	s_mov_b32 s8, 0x368000
	s_nop 0
	v_addc_co_u32_e32 v9, vcc, 0, v7, vcc
	global_load_dword v33, v[8:9], off nt
	v_add_co_u32_e32 v8, vcc, s8, v6
	s_mov_b32 s8, 0x370000
	s_nop 0
	v_addc_co_u32_e32 v9, vcc, 0, v7, vcc
	global_load_dword v34, v[8:9], off nt
	v_add_co_u32_e32 v8, vcc, s8, v6
	s_mov_b32 s8, 0x378000
	s_nop 0
	v_addc_co_u32_e32 v9, vcc, 0, v7, vcc
	global_load_dword v30, v[8:9], off nt
	v_add_co_u32_e32 v8, vcc, s8, v6
	s_mov_b32 s8, 0x380000
	s_nop 0
	v_addc_co_u32_e32 v9, vcc, 0, v7, vcc
	global_load_dword v31, v[8:9], off nt
	v_add_co_u32_e32 v8, vcc, s8, v6
	s_mov_b32 s8, 0x388000
	s_nop 0
	v_addc_co_u32_e32 v9, vcc, 0, v7, vcc
	global_load_dword v24, v[8:9], off nt
	v_add_co_u32_e32 v8, vcc, s8, v6
	s_mov_b32 s8, 0x390000
	s_nop 0
	v_addc_co_u32_e32 v9, vcc, 0, v7, vcc
	global_load_dword v26, v[8:9], off nt
	v_add_co_u32_e32 v8, vcc, s8, v6
	s_mov_b32 s8, 0x398000
	s_nop 0
	v_addc_co_u32_e32 v9, vcc, 0, v7, vcc
	global_load_dword v22, v[8:9], off nt
	v_add_co_u32_e32 v8, vcc, s8, v6
	s_mov_b32 s8, 0x3a0000
	s_nop 0
	v_addc_co_u32_e32 v9, vcc, 0, v7, vcc
	global_load_dword v28, v[8:9], off nt
	v_add_co_u32_e32 v8, vcc, s8, v6
	s_mov_b32 s8, 0x3a8000
	s_nop 0
	v_addc_co_u32_e32 v9, vcc, 0, v7, vcc
	global_load_dword v29, v[8:9], off nt
; DI bf16_t f2bf(float f) { return (bf16_t)(pk2(f, 0.f) & 0xffffu); }
; DI void gla_scan(const Params& p, int G, LAS unsigned char* lds) {
;     ...
;         for (int n0 = 0; n0 < 128; n0 += 64) { float dv[64];
; #pragma unroll
;             for (int j2 = 0; j2 < 64; ++j2) dv[j2] = __builtin_nontemporal_load(dp + (size_t)(n0 + j2) * 8192);
; #pragma unroll
;             for (int j2 = 0; j2 < 64; ++j2) { sp[(size_t)(n0 + j2) * 8192] = f2bf(st); st = dl[(n0 + j2) * 64 + k] * st + dv[j2]; } }
	v_add_co_u32_e32 v8, vcc, s8, v6
	s_mov_b32 s8, 0x3b0000
	s_nop 0
	v_addc_co_u32_e32 v9, vcc, 0, v7, vcc
	global_load_dword v32, v[8:9], off nt
	v_add_co_u32_e32 v8, vcc, s8, v6
	s_mov_b32 s8, 0x3b8000
	s_nop 0
	v_addc_co_u32_e32 v9, vcc, 0, v7, vcc
	global_load_dword v25, v[8:9], off nt
	v_add_co_u32_e32 v8, vcc, s8, v6
	s_mov_b32 s8, 0x3c0000
	s_nop 0
	v_addc_co_u32_e32 v9, vcc, 0, v7, vcc
	global_load_dword v27, v[8:9], off nt
	v_add_co_u32_e32 v8, vcc, s8, v6
	s_mov_b32 s8, 0x3c8000
	s_nop 0
	v_addc_co_u32_e32 v9, vcc, 0, v7, vcc
	global_load_dword v20, v[8:9], off nt
	v_add_co_u32_e32 v8, vcc, s8, v6
	s_mov_b32 s8, 0x3d0000
	s_nop 0
	v_addc_co_u32_e32 v9, vcc, 0, v7, vcc
	global_load_dword v21, v[8:9], off nt
	v_add_co_u32_e32 v8, vcc, s8, v6
	s_mov_b32 s8, 0x3d8000
	s_nop 0
	v_addc_co_u32_e32 v9, vcc, 0, v7, vcc
	global_load_dword v18, v[8:9], off nt
	v_add_co_u32_e32 v8, vcc, s8, v6
	s_mov_b32 s8, 0x3e0000
	s_nop 0
	v_addc_co_u32_e32 v9, vcc, 0, v7, vcc
	global_load_dword v17, v[8:9], off nt
	v_add_co_u32_e32 v8, vcc, s8, v6
	s_mov_b32 s8, 0x3e8000
	s_nop 0
	v_addc_co_u32_e32 v9, vcc, 0, v7, vcc
	v_add_co_u32_e32 v78, vcc, s8, v6
	s_mov_b32 s8, 0x3f0000
	s_nop 0
	v_addc_co_u32_e32 v79, vcc, 0, v7, vcc
	v_add_co_u32_e32 v6, vcc, s8, v6
	global_load_dword v9, v[8:9], off nt
	s_nop 0
	v_addc_co_u32_e32 v7, vcc, 0, v7, vcc
	global_load_dword v23, v[6:7], off nt
	v_add_co_u32_e32 v6, vcc, s70, v4
	global_load_dword v8, v[78:79], off nt
	v_cvt_pk_bf16_f32 v78, v19, s0
	v_addc_co_u32_e32 v7, vcc, 0, v5, vcc
	global_store_short v[6:7], v78, off
	s_mov_b32 s8, 0x104000
	v_add_co_u32_e32 v78, vcc, s8, v4
	s_mov_b32 s8, 0x10c000
	s_waitcnt vmcnt(62) lgkmcnt(0)
	v_fmac_f32_e32 v0, v19, v98
	v_cvt_pk_bf16_f32 v6, v0, s0
	v_addc_co_u32_e32 v79, vcc, 0, v5, vcc
	global_store_short v[78:79], v6, off
	v_fmac_f32_e32 v77, v0, v99
	v_add_co_u32_e32 v6, vcc, s71, v4
	v_cvt_pk_bf16_f32 v0, v77, s0
	s_nop 0
	v_addc_co_u32_e32 v7, vcc, 0, v5, vcc
	global_store_short v[6:7], v0, off
	v_add_co_u32_e32 v78, vcc, s8, v4
	s_mov_b32 s8, 0x114000
	s_nop 0
	v_addc_co_u32_e32 v79, vcc, 0, v5, vcc
	s_waitcnt vmcnt(62) lgkmcnt(0)
	v_fmac_f32_e32 v75, v77, v100
	v_cvt_pk_bf16_f32 v0, v75, s0
	v_fmac_f32_e32 v76, v75, v101
	v_add_co_u32_e32 v6, vcc, s72, v4
	global_store_short v[78:79], v0, off
	v_cvt_pk_bf16_f32 v0, v76, s0
	v_addc_co_u32_e32 v7, vcc, 0, v5, vcc
	global_store_short v[6:7], v0, off
	s_waitcnt vmcnt(62) lgkmcnt(0)
	v_fmac_f32_e32 v73, v76, v102
	v_add_co_u32_e32 v76, vcc, s8, v4
	v_cvt_pk_bf16_f32 v0, v73, s0
	s_nop 0
	v_addc_co_u32_e32 v77, vcc, 0, v5, vcc
	v_fmac_f32_e32 v74, v73, v103
	v_add_co_u32_e32 v6, vcc, s73, v4
	global_store_short v[76:77], v0, off
	v_cvt_pk_bf16_f32 v0, v74, s0
	v_addc_co_u32_e32 v7, vcc, 0, v5, vcc
	global_store_short v[6:7], v0, off
	s_mov_b32 s8, 0x11c000
	s_waitcnt vmcnt(62) lgkmcnt(0)
	v_fmac_f32_e32 v71, v74, v104
	v_add_co_u32_e32 v74, vcc, s8, v4
	v_cvt_pk_bf16_f32 v0, v71, s0
	s_nop 0
	v_addc_co_u32_e32 v75, vcc, 0, v5, vcc
	v_fmac_f32_e32 v72, v71, v105
	v_add_co_u32_e32 v6, vcc, s78, v4
	global_store_short v[74:75], v0, off
	v_cvt_pk_bf16_f32 v0, v72, s0
	v_addc_co_u32_e32 v7, vcc, 0, v5, vcc
	global_store_short v[6:7], v0, off
	s_mov_b32 s8, 0x124000
	s_waitcnt vmcnt(62) lgkmcnt(0)
	v_fmac_f32_e32 v68, v72, v106
	v_add_co_u32_e32 v72, vcc, s8, v4
	v_cvt_pk_bf16_f32 v0, v68, s0
	s_nop 0
	v_addc_co_u32_e32 v73, vcc, 0, v5, vcc
	v_fmac_f32_e32 v69, v68, v107
	v_add_co_u32_e32 v6, vcc, s79, v4
	global_store_short v[72:73], v0, off
	v_cvt_pk_bf16_f32 v0, v69, s0
	v_addc_co_u32_e32 v7, vcc, 0, v5, vcc
	global_store_short v[6:7], v0, off
	s_mov_b32 s8, 0x12c000
	v_add_co_u32_e32 v68, vcc, s8, v4
	s_mov_b32 s8, 0x134000
	s_waitcnt vmcnt(62) lgkmcnt(0)
	v_fmac_f32_e32 v62, v69, v108
	v_addc_co_u32_e32 v69, vcc, 0, v5, vcc
	v_cvt_pk_bf16_f32 v0, v62, s0
	v_fmac_f32_e32 v63, v62, v109
	v_add_co_u32_e32 v6, vcc, s81, v4
	global_store_short v[68:69], v0, off
	v_cvt_pk_bf16_f32 v0, v63, s0
	v_addc_co_u32_e32 v7, vcc, 0, v5, vcc
	global_store_short v[6:7], v0, off
	v_add_co_u32_e32 v62, vcc, s8, v4
	s_mov_b32 s8, 0x13c000
	s_waitcnt vmcnt(62) lgkmcnt(0)
	v_fmac_f32_e32 v59, v63, v110
	v_addc_co_u32_e32 v63, vcc, 0, v5, vcc
	v_cvt_pk_bf16_f32 v0, v59, s0
	v_fmac_f32_e32 v70, v59, v111
	v_add_co_u32_e32 v6, vcc, s83, v4
	global_store_short v[62:63], v0, off
	v_cvt_pk_bf16_f32 v0, v70, s0
	v_addc_co_u32_e32 v7, vcc, 0, v5, vcc
	global_store_short v[6:7], v0, off
	v_add_co_u32_e32 v62, vcc, s8, v4
	s_mov_b32 s8, 0x144000
	s_nop 0
	v_addc_co_u32_e32 v63, vcc, 0, v5, vcc
	s_waitcnt vmcnt(62) lgkmcnt(0)
	v_fmac_f32_e32 v66, v70, v112
	v_cvt_pk_bf16_f32 v0, v66, s0
	v_fmac_f32_e32 v67, v66, v113
	v_add_co_u32_e32 v6, vcc, s84, v4
	global_store_short v[62:63], v0, off
	v_cvt_pk_bf16_f32 v0, v67, s0
	v_addc_co_u32_e32 v7, vcc, 0, v5, vcc
	global_store_short v[6:7], v0, off
	v_add_co_u32_e32 v62, vcc, s8, v4
	s_mov_b32 s8, 0x14c000
	s_nop 0
	v_addc_co_u32_e32 v63, vcc, 0, v5, vcc
	s_waitcnt vmcnt(62) lgkmcnt(0)
	v_fmac_f32_e32 v64, v67, v114
	v_cvt_pk_bf16_f32 v0, v64, s0
	v_fmac_f32_e32 v65, v64, v115
	v_add_co_u32_e32 v6, vcc, s85, v4
	global_store_short v[62:63], v0, off
	v_cvt_pk_bf16_f32 v0, v65, s0
	v_addc_co_u32_e32 v7, vcc, 0, v5, vcc
	global_store_short v[6:7], v0, off
	v_add_co_u32_e32 v62, vcc, s8, v4
	s_mov_b32 s8, 0x154000
	s_nop 0
	v_addc_co_u32_e32 v63, vcc, 0, v5, vcc
	s_waitcnt vmcnt(62) lgkmcnt(0)
	v_fmac_f32_e32 v60, v65, v116
	v_cvt_pk_bf16_f32 v0, v60, s0
	v_fmac_f32_e32 v61, v60, v117
	v_add_co_u32_e32 v6, vcc, s87, v4
	global_store_short v[62:63], v0, off
	v_cvt_pk_bf16_f32 v0, v61, s0
	v_addc_co_u32_e32 v7, vcc, 0, v5, vcc
	global_store_short v[6:7], v0, off
	v_add_co_u32_e32 v60, vcc, s8, v4
	s_mov_b32 s8, 0x15c000
	s_waitcnt vmcnt(62) lgkmcnt(0)
; DI bf16_t f2bf(float f) { return (bf16_t)(pk2(f, 0.f) & 0xffffu); }
; DI void gla_scan(const Params& p, int G, LAS unsigned char* lds) {
;     ...
;             for (int j2 = 0; j2 < 64; ++j2) dv[j2] = __builtin_nontemporal_load(dp + (size_t)(n0 + j2) * 8192);
; #pragma unroll
;             for (int j2 = 0; j2 < 64; ++j2) { sp[(size_t)(n0 + j2) * 8192] = f2bf(st); st = dl[(n0 + j2) * 64 + k] * st + dv[j2]; } }
	v_fmac_f32_e32 v57, v61, v118
	v_addc_co_u32_e32 v61, vcc, 0, v5, vcc
	v_cvt_pk_bf16_f32 v0, v57, s0
	v_fmac_f32_e32 v58, v57, v119
	v_add_co_u32_e32 v6, vcc, s88, v4
	global_store_short v[60:61], v0, off
	v_cvt_pk_bf16_f32 v0, v58, s0
	v_addc_co_u32_e32 v7, vcc, 0, v5, vcc
	global_store_short v[6:7], v0, off
	s_waitcnt vmcnt(62) lgkmcnt(0)
	v_fmac_f32_e32 v55, v58, v120
	v_add_co_u32_e32 v58, vcc, s8, v4
	v_cvt_pk_bf16_f32 v0, v55, s0
	s_nop 0
	v_addc_co_u32_e32 v59, vcc, 0, v5, vcc
	v_fmac_f32_e32 v56, v55, v121
	v_add_co_u32_e32 v6, vcc, s89, v4
	global_store_short v[58:59], v0, off
	v_cvt_pk_bf16_f32 v0, v56, s0
	v_addc_co_u32_e32 v7, vcc, 0, v5, vcc
	global_store_short v[6:7], v0, off
	s_mov_b32 s8, 0x164000
	s_waitcnt vmcnt(62) lgkmcnt(0)
	v_fmac_f32_e32 v53, v56, v122
	v_add_co_u32_e32 v56, vcc, s8, v4
	v_cvt_pk_bf16_f32 v0, v53, s0
	s_nop 0
	v_addc_co_u32_e32 v57, vcc, 0, v5, vcc
	v_fmac_f32_e32 v54, v53, v123
	v_add_co_u32_e32 v6, vcc, s35, v4
	global_store_short v[56:57], v0, off
	v_cvt_pk_bf16_f32 v0, v54, s0
	v_addc_co_u32_e32 v7, vcc, 0, v5, vcc
	global_store_short v[6:7], v0, off
	s_mov_b32 s8, 0x16c000
	s_waitcnt vmcnt(62) lgkmcnt(0)
	v_fmac_f32_e32 v51, v54, v124
	v_add_co_u32_e32 v54, vcc, s8, v4
	v_cvt_pk_bf16_f32 v0, v51, s0
	s_nop 0
	v_addc_co_u32_e32 v55, vcc, 0, v5, vcc
	v_fmac_f32_e32 v52, v51, v125
	v_add_co_u32_e32 v6, vcc, s86, v4
	global_store_short v[54:55], v0, off
	v_cvt_pk_bf16_f32 v0, v52, s0
	v_addc_co_u32_e32 v7, vcc, 0, v5, vcc
	global_store_short v[6:7], v0, off
	s_mov_b32 s8, 0x174000
	s_waitcnt vmcnt(62) lgkmcnt(0)
	v_fmac_f32_e32 v49, v52, v126
	v_add_co_u32_e32 v52, vcc, s8, v4
	v_cvt_pk_bf16_f32 v0, v49, s0
	s_nop 0
	v_addc_co_u32_e32 v53, vcc, 0, v5, vcc
	v_fmac_f32_e32 v50, v49, v127
	v_add_co_u32_e32 v6, vcc, s90, v4
	global_store_short v[52:53], v0, off
	v_cvt_pk_bf16_f32 v0, v50, s0
	v_addc_co_u32_e32 v7, vcc, 0, v5, vcc
	global_store_short v[6:7], v0, off
	s_mov_b32 s8, 0x17c000
	s_waitcnt vmcnt(62) lgkmcnt(0)
	v_fmac_f32_e32 v47, v50, v128
	v_add_co_u32_e32 v50, vcc, s8, v4
	v_cvt_pk_bf16_f32 v0, v47, s0
	s_nop 0
	v_addc_co_u32_e32 v51, vcc, 0, v5, vcc
	v_fmac_f32_e32 v48, v47, v129
	v_add_co_u32_e32 v6, vcc, s91, v4
	global_store_short v[50:51], v0, off
	v_cvt_pk_bf16_f32 v0, v48, s0
	v_addc_co_u32_e32 v7, vcc, 0, v5, vcc
	global_store_short v[6:7], v0, off
	s_mov_b32 s8, 0x184000
	s_waitcnt vmcnt(62) lgkmcnt(0)
	v_fmac_f32_e32 v45, v48, v130
	v_add_co_u32_e32 v48, vcc, s8, v4
	v_cvt_pk_bf16_f32 v0, v45, s0
	s_nop 0
	v_addc_co_u32_e32 v49, vcc, 0, v5, vcc
	v_fmac_f32_e32 v46, v45, v131
	v_add_co_u32_e32 v6, vcc, s18, v4
	global_store_short v[48:49], v0, off
	v_cvt_pk_bf16_f32 v0, v46, s0
	v_addc_co_u32_e32 v7, vcc, 0, v5, vcc
	global_store_short v[6:7], v0, off
	s_mov_b32 s8, 0x18c000
	s_waitcnt vmcnt(62) lgkmcnt(0)
	v_fmac_f32_e32 v43, v46, v132
	v_add_co_u32_e32 v46, vcc, s8, v4
	v_cvt_pk_bf16_f32 v0, v43, s0
	s_nop 0
	v_addc_co_u32_e32 v47, vcc, 0, v5, vcc
	v_fmac_f32_e32 v44, v43, v133
	v_add_co_u32_e32 v6, vcc, s19, v4
	global_store_short v[46:47], v0, off
	v_cvt_pk_bf16_f32 v0, v44, s0
	v_addc_co_u32_e32 v7, vcc, 0, v5, vcc
	global_store_short v[6:7], v0, off
	s_mov_b32 s8, 0x194000
	s_waitcnt vmcnt(62) lgkmcnt(0)
	v_fmac_f32_e32 v41, v44, v134
	v_add_co_u32_e32 v44, vcc, s8, v4
	v_cvt_pk_bf16_f32 v0, v41, s0
	s_nop 0
	v_addc_co_u32_e32 v45, vcc, 0, v5, vcc
	v_fmac_f32_e32 v42, v41, v135
	v_add_co_u32_e32 v6, vcc, s36, v4
	global_store_short v[44:45], v0, off
	v_cvt_pk_bf16_f32 v0, v42, s0
	v_addc_co_u32_e32 v7, vcc, 0, v5, vcc
	global_store_short v[6:7], v0, off
	s_mov_b32 s8, 0x19c000
	s_waitcnt vmcnt(62) lgkmcnt(0)
	v_fmac_f32_e32 v39, v42, v136
	v_add_co_u32_e32 v42, vcc, s8, v4
	v_cvt_pk_bf16_f32 v0, v39, s0
	s_nop 0
	v_addc_co_u32_e32 v43, vcc, 0, v5, vcc
	v_fmac_f32_e32 v40, v39, v137
	v_add_co_u32_e32 v6, vcc, s37, v4
	global_store_short v[42:43], v0, off
	v_cvt_pk_bf16_f32 v0, v40, s0
	v_addc_co_u32_e32 v7, vcc, 0, v5, vcc
	global_store_short v[6:7], v0, off
	s_mov_b32 s8, 0x1a4000
	s_waitcnt vmcnt(62) lgkmcnt(0)
	v_fmac_f32_e32 v37, v40, v138
	v_add_co_u32_e32 v40, vcc, s8, v4
	v_cvt_pk_bf16_f32 v0, v37, s0
	s_nop 0
	v_addc_co_u32_e32 v41, vcc, 0, v5, vcc
	v_fmac_f32_e32 v38, v37, v139
	v_add_co_u32_e32 v6, vcc, s6, v4
	global_store_short v[40:41], v0, off
	v_cvt_pk_bf16_f32 v0, v38, s0
	v_addc_co_u32_e32 v7, vcc, 0, v5, vcc
	global_store_short v[6:7], v0, off
	s_mov_b32 s8, 0x1ac000
	s_waitcnt vmcnt(62) lgkmcnt(0)
; DI bf16_t f2bf(float f) { return (bf16_t)(pk2(f, 0.f) & 0xffffu); }
; DI void gla_scan(const Params& p, int G, LAS unsigned char* lds) {
;     ...
;         for (int n0 = 0; n0 < 128; n0 += 64) { float dv[64];
; #pragma unroll
;             for (int j2 = 0; j2 < 64; ++j2) dv[j2] = __builtin_nontemporal_load(dp + (size_t)(n0 + j2) * 8192);
; #pragma unroll
;             for (int j2 = 0; j2 < 64; ++j2) { sp[(size_t)(n0 + j2) * 8192] = f2bf(st); st = dl[(n0 + j2) * 64 + k] * st + dv[j2]; } }
	v_fmac_f32_e32 v35, v38, v140
	v_add_co_u32_e32 v38, vcc, s8, v4
	v_cvt_pk_bf16_f32 v0, v35, s0
	s_nop 0
	v_addc_co_u32_e32 v39, vcc, 0, v5, vcc
	v_fmac_f32_e32 v36, v35, v141
	v_add_co_u32_e32 v6, vcc, s7, v4
	global_store_short v[38:39], v0, off
	v_cvt_pk_bf16_f32 v0, v36, s0
	v_addc_co_u32_e32 v7, vcc, 0, v5, vcc
	global_store_short v[6:7], v0, off
	s_mov_b32 s8, 0x1b4000
	s_waitcnt vmcnt(62) lgkmcnt(0)
	v_fmac_f32_e32 v33, v36, v142
	v_add_co_u32_e32 v36, vcc, s8, v4
	v_cvt_pk_bf16_f32 v0, v33, s0
	s_nop 0
	v_addc_co_u32_e32 v37, vcc, 0, v5, vcc
	v_fmac_f32_e32 v34, v33, v143
	v_add_co_u32_e32 v6, vcc, s0, v4
	global_store_short v[36:37], v0, off
	v_cvt_pk_bf16_f32 v0, v34, s0
	v_addc_co_u32_e32 v7, vcc, 0, v5, vcc
	global_store_short v[6:7], v0, off
	s_mov_b32 s8, 0x1bc000
	s_waitcnt vmcnt(62) lgkmcnt(0)
	v_fmac_f32_e32 v30, v34, v144
	v_add_co_u32_e32 v34, vcc, s8, v4
	v_cvt_pk_bf16_f32 v0, v30, s0
	s_nop 0
	v_addc_co_u32_e32 v35, vcc, 0, v5, vcc
	v_fmac_f32_e32 v31, v30, v145
	v_add_co_u32_e32 v6, vcc, s1, v4
	global_store_short v[34:35], v0, off
	v_cvt_pk_bf16_f32 v0, v31, s0
	v_addc_co_u32_e32 v7, vcc, 0, v5, vcc
	global_store_short v[6:7], v0, off
	s_mov_b32 s8, 0x1c4000
	v_add_co_u32_e32 v30, vcc, s8, v4
	s_mov_b32 s8, 0x1cc000
	s_waitcnt vmcnt(62) lgkmcnt(0)
	v_fmac_f32_e32 v24, v31, v146
	v_addc_co_u32_e32 v31, vcc, 0, v5, vcc
	v_cvt_pk_bf16_f32 v0, v24, s0
	v_fmac_f32_e32 v26, v24, v147
	v_add_co_u32_e32 v6, vcc, s4, v4
	global_store_short v[30:31], v0, off
	v_cvt_pk_bf16_f32 v0, v26, s0
	v_addc_co_u32_e32 v7, vcc, 0, v5, vcc
	global_store_short v[6:7], v0, off
	v_add_co_u32_e32 v30, vcc, s8, v4
	s_mov_b32 s8, 0x1d4000
	s_nop 0
	v_addc_co_u32_e32 v31, vcc, 0, v5, vcc
	s_waitcnt vmcnt(62) lgkmcnt(0)
	v_fmac_f32_e32 v22, v26, v148
	v_cvt_pk_bf16_f32 v0, v22, s0
	v_fmac_f32_e32 v28, v22, v149
	v_add_co_u32_e32 v6, vcc, s5, v4
	global_store_short v[30:31], v0, off
	v_cvt_pk_bf16_f32 v0, v28, s0
	v_addc_co_u32_e32 v7, vcc, 0, v5, vcc
	global_store_short v[6:7], v0, off
	v_add_co_u32_e32 v30, vcc, s8, v4
	s_mov_b32 s8, 0x1dc000
	s_nop 0
	v_addc_co_u32_e32 v31, vcc, 0, v5, vcc
	s_waitcnt vmcnt(62) lgkmcnt(0)
	v_fmac_f32_e32 v29, v28, v150
	v_cvt_pk_bf16_f32 v0, v29, s0
	v_fmac_f32_e32 v32, v29, v151
	v_add_co_u32_e32 v6, vcc, s92, v4
	global_store_short v[30:31], v0, off
	v_cvt_pk_bf16_f32 v0, v32, s0
	v_addc_co_u32_e32 v7, vcc, 0, v5, vcc
	global_store_short v[6:7], v0, off
	v_add_co_u32_e32 v28, vcc, s8, v4
	s_mov_b32 s8, 0x1e4000
	s_nop 0
	v_addc_co_u32_e32 v29, vcc, 0, v5, vcc
	s_waitcnt vmcnt(62) lgkmcnt(0)
	v_fmac_f32_e32 v25, v32, v152
	v_cvt_pk_bf16_f32 v0, v25, s0
	v_fmac_f32_e32 v27, v25, v153
	v_add_co_u32_e32 v6, vcc, s93, v4
	global_store_short v[28:29], v0, off
	v_cvt_pk_bf16_f32 v0, v27, s0
	v_addc_co_u32_e32 v7, vcc, 0, v5, vcc
	global_store_short v[6:7], v0, off
	v_add_co_u32_e32 v24, vcc, s8, v4
	s_mov_b32 s8, 0x1ec000
	s_nop 0
	v_addc_co_u32_e32 v25, vcc, 0, v5, vcc
	s_waitcnt vmcnt(62) lgkmcnt(0)
	v_fmac_f32_e32 v20, v27, v154
	v_cvt_pk_bf16_f32 v0, v20, s0
	v_fmac_f32_e32 v21, v20, v155
	v_add_co_u32_e32 v6, vcc, s12, v4
	global_store_short v[24:25], v0, off
	v_cvt_pk_bf16_f32 v0, v21, s0
	v_addc_co_u32_e32 v7, vcc, 0, v5, vcc
	global_store_short v[6:7], v0, off
	v_add_co_u32_e32 v20, vcc, s8, v4
	s_waitcnt vmcnt(62) lgkmcnt(0)
	v_fmac_f32_e32 v18, v21, v156
	v_addc_co_u32_e32 v21, vcc, 0, v5, vcc
	v_cvt_pk_bf16_f32 v0, v18, s0
	v_fmac_f32_e32 v17, v18, v157
	v_add_co_u32_e32 v6, vcc, s13, v4
	global_store_short v[20:21], v0, off
	v_cvt_pk_bf16_f32 v0, v17, s0
	v_addc_co_u32_e32 v7, vcc, 0, v5, vcc
	global_store_short v[6:7], v0, off
	v_add_co_u32_e32 v18, vcc, 0x1f4000, v4
	s_waitcnt vmcnt(62) lgkmcnt(0)
	v_fmac_f32_e32 v9, v17, v158
	v_addc_co_u32_e32 v19, vcc, 0, v5, vcc
	v_cvt_pk_bf16_f32 v0, v9, s0
	s_waitcnt vmcnt(61)
	v_fmac_f32_e32 v8, v9, v159
	v_add_co_u32_e32 v6, vcc, 0x1f8000, v4
	global_store_short v[18:19], v0, off
	v_cvt_pk_bf16_f32 v0, v8, s0
	v_addc_co_u32_e32 v7, vcc, 0, v5, vcc
	global_store_short v[6:7], v0, off
	v_add_co_u32_e32 v4, vcc, 0x1fc000, v4
	s_waitcnt lgkmcnt(0)
	v_fmac_f32_e32 v23, v8, v160
	v_cvt_pk_bf16_f32 v0, v23, s0
	v_addc_co_u32_e32 v5, vcc, 0, v5, vcc
	global_store_short v[4:5], v0, off
	s_cbranch_scc1 .LBB0_434
	v_readlane_b32 s90, v253, 46
	v_readlane_b32 s91, v253, 47
	v_readlane_b32 s92, v254, 23
	v_readlane_b32 s86, v253, 48
	v_readlane_b32 s93, v254, 24
